# XCD barrier: waiters spin on the top-level arrival counter itself (no separate generation bump before release)
# speedup vs baseline: 1.0194x; 1.0004x over previous
; __device__ __forceinline__ unsigned xb_ld(unsigned* p)              { return __hip_atomic_load(p, __ATOMIC_RELAXED, __HIP_MEMORY_SCOPE_AGENT); }
; __device__ __forceinline__ unsigned xb_add(unsigned* p, unsigned v) { return __hip_atomic_fetch_add(p, v, __ATOMIC_RELAXED, __HIP_MEMORY_SCOPE_AGENT); }
; #define XB_SPIN(cond, bar) do { unsigned _sp = 0; while (cond) { __builtin_amdgcn_s_sleep(1); \
;     if ((++_sp & 255u) == 0u) { if (xb_ld(&(bar)[XB_TMO])) break; if (_sp > XB_SPIN_CAP) { atomicAdd(&(bar)[XB_TMO], 1u); break; } } } } while (0)
; __device__ __forceinline__ void xcd_barrier(const XcdBarrier& b, int wv) {
;     ...
;         const unsigned old = xb_add(&bar[XB_XSUB(bx)], 1u);
;         const unsigned gen = old / nloc;
;         if (old + 1u == (gen + 1u) * nloc) {
;     ...
;             XB_SPIN(xb_ld(&bar[XB_XGEN(bx)]) == gen, bar);
.LBB0_142:
	s_or_b64 exec, exec, s[6:7]
	v_cvt_f32_u32_e32 v4, v2
	s_waitcnt vmcnt(0)
	v_readfirstlane_b32 s4, v3
	v_sub_u32_e32 v3, 0, v2
	v_rcp_iflag_f32_e32 v4, v4
	v_add_u32_e32 v5, s4, v1
	v_mul_f32_e32 v4, 0x4f7ffffe, v4
	v_cvt_u32_f32_e32 v4, v4
	v_mul_lo_u32 v1, v3, v4
	v_mul_hi_u32 v1, v4, v1
	v_add_u32_e32 v1, v4, v1
	v_mul_hi_u32 v1, v5, v1
	v_mul_lo_u32 v3, v1, v2
	v_sub_u32_e32 v3, v5, v3
	v_add_u32_e32 v4, 1, v1
	v_cmp_ge_u32_e32 vcc, v3, v2
	s_nop 1
	v_cndmask_b32_e32 v1, v1, v4, vcc
	v_sub_u32_e32 v4, v3, v2
	v_cndmask_b32_e32 v3, v3, v4, vcc
	v_add_u32_e32 v4, 1, v1
	v_cmp_ge_u32_e32 vcc, v3, v2
	v_add_u32_e32 v3, 1, v5
	s_nop 0
	v_cndmask_b32_e32 v1, v1, v4, vcc
	v_mul_lo_u32 v4, v2, v1
	v_add_u32_e32 v2, v4, v2
	v_cmp_ne_u32_e32 vcc, v3, v2
	s_and_saveexec_b64 s[4:5], vcc
	s_xor_b64 s[4:5], exec, s[4:5]
	s_cbranch_execz .LBB0_156
	s_movk_i32 s6, 0xd00
	v_mad_u32_u24 v2, v1, v0, v0
	s_nop 0
	v_readfirstlane_b32 s98, v2
	s_mov_b32 s7, 0
	s_lshl_b64 s[6:7], s[6:7], 2
	s_add_u32 s10, s82, s6
	s_addc_u32 s11, s83, s7
	s_waitcnt lgkmcnt(0)
	v_mov_b32_e32 v0, 0
	global_load_dword v2, v0, s[10:11] sc1
	s_waitcnt vmcnt(0)
	v_cmp_gt_u32_e32 vcc, s98, v2
	s_and_saveexec_b64 s[6:7], vcc
	s_cbranch_execz .LBB0_155
	s_add_u32 s8, s30, 0x3e9200
	s_addc_u32 s9, s31, 0
	s_mov_b32 s36, 1
	s_mov_b64 s[12:13], 0
	s_branch .LBB0_146

; __device__ __forceinline__ unsigned xb_ld(unsigned* p)              { return __hip_atomic_load(p, __ATOMIC_RELAXED, __HIP_MEMORY_SCOPE_AGENT); }
; #define XB_SPIN(cond, bar) do { unsigned _sp = 0; while (cond) { __builtin_amdgcn_s_sleep(1); \
;     if ((++_sp & 255u) == 0u) { if (xb_ld(&(bar)[XB_TMO])) break; if (_sp > XB_SPIN_CAP) { atomicAdd(&(bar)[XB_TMO], 1u); break; } } } } while (0)
; __device__ __forceinline__ void xcd_barrier(const XcdBarrier& b, int wv) {
;     ...
;             XB_SPIN(xb_ld(&bar[XB_XGEN(bx)]) == gen, bar);
.LBB0_148:
	global_load_dword v2, v0, s[10:11] sc1
	s_add_i32 s36, s36, 1
	s_mov_b64 s[20:21], -1
	s_waitcnt vmcnt(0)
	v_cmp_le_u32_e32 vcc, s98, v2
	s_orn2_b64 s[16:17], vcc, exec
	s_branch .LBB0_145

; __device__ __forceinline__ unsigned xb_ld(unsigned* p)              { return __hip_atomic_load(p, __ATOMIC_RELAXED, __HIP_MEMORY_SCOPE_AGENT); }
; __device__ __forceinline__ unsigned xb_add(unsigned* p, unsigned v) { return __hip_atomic_fetch_add(p, v, __ATOMIC_RELAXED, __HIP_MEMORY_SCOPE_AGENT); }
; #define XB_SPIN(cond, bar) do { unsigned _sp = 0; while (cond) { __builtin_amdgcn_s_sleep(1); \
;     if ((++_sp & 255u) == 0u) { if (xb_ld(&(bar)[XB_TMO])) break; if (_sp > XB_SPIN_CAP) { atomicAdd(&(bar)[XB_TMO], 1u); break; } } } } while (0)
; __device__ __forceinline__ void xcd_barrier(const XcdBarrier& b, int wv) {
;     ...
;             const unsigned og = xb_add(&bar[XB_TOP], 1u);
;             const unsigned tg = og / nx;
;             if (og + 1u == (tg + 1u) * nx) xb_add(&bar[XB_TOPGEN], 1u);
;             else XB_SPIN(xb_ld(&bar[XB_TOPGEN]) == tg, bar);
.LBB0_159:
	s_or_b64 exec, exec, s[6:7]
	v_cvt_f32_u32_e32 v3, v0
	s_waitcnt vmcnt(0)
	v_readfirstlane_b32 s4, v2
	s_add_u32 s6, s30, 0x3ec500
	s_addc_u32 s7, s31, 0
	v_rcp_iflag_f32_e32 v3, v3
	v_add_u32_e32 v1, s4, v1
	v_add_u32_e32 v4, 1, v1
	s_mov_b64 s[8:9], -1
	v_mul_f32_e32 v2, 0x4f7ffffe, v3
	v_cvt_u32_f32_e32 v2, v2
	v_sub_u32_e32 v3, 0, v0
	v_mul_lo_u32 v3, v3, v2
	v_mul_hi_u32 v3, v2, v3
	v_add_u32_e32 v2, v2, v3
	v_mul_hi_u32 v2, v1, v2
	v_mul_lo_u32 v3, v2, v0
	v_sub_u32_e32 v1, v1, v3
	v_add_u32_e32 v5, 1, v2
	v_cmp_ge_u32_e32 vcc, v1, v0
	v_sub_u32_e32 v3, v1, v0
	s_nop 0
	v_cndmask_b32_e32 v2, v2, v5, vcc
	v_cndmask_b32_e32 v1, v1, v3, vcc
	v_add_u32_e32 v3, 1, v2
	v_cmp_ge_u32_e32 vcc, v1, v0
	s_nop 1
	v_cndmask_b32_e32 v2, v2, v3, vcc
	v_mul_lo_u32 v1, v0, v2
	v_add_u32_e32 v0, v1, v0
	v_cmp_ne_u32_e32 vcc, v4, v0
	v_readfirstlane_b32 s98, v0
	v_mov_b64_e32 v[0:1], s[6:7]
	s_and_saveexec_b64 s[4:5], vcc
	s_cbranch_execz .LBB0_171
	v_mov_b32_e32 v0, 0
	global_load_dword v1, v0, s[6:7] offset:-256 sc1
	s_mov_b64 s[12:13], 0
	s_waitcnt vmcnt(0)
	v_cmp_gt_u32_e32 vcc, s98, v1
	s_and_saveexec_b64 s[10:11], vcc
	s_cbranch_execz .LBB0_170
	s_add_u32 s8, s30, 0x3e9200
	s_addc_u32 s9, s31, 0
	s_mov_b32 s36, 1
	s_branch .LBB0_163

; __device__ __forceinline__ unsigned xb_ld(unsigned* p)              { return __hip_atomic_load(p, __ATOMIC_RELAXED, __HIP_MEMORY_SCOPE_AGENT); }
; #define XB_SPIN(cond, bar) do { unsigned _sp = 0; while (cond) { __builtin_amdgcn_s_sleep(1); \
;     if ((++_sp & 255u) == 0u) { if (xb_ld(&(bar)[XB_TMO])) break; if (_sp > XB_SPIN_CAP) { atomicAdd(&(bar)[XB_TMO], 1u); break; } } } } while (0)
; __device__ __forceinline__ void xcd_barrier(const XcdBarrier& b, int wv) {
;     ...
;             else XB_SPIN(xb_ld(&bar[XB_TOPGEN]) == tg, bar);
.LBB0_165:
	global_load_dword v1, v0, s[6:7] offset:-256 sc1
	s_add_i32 s36, s36, 1
	s_mov_b64 s[16:17], -1
	s_waitcnt vmcnt(0)
	v_cmp_le_u32_e32 vcc, s98, v1
	s_orn2_b64 s[22:23], vcc, exec
	s_branch .LBB0_162

; __device__ __forceinline__ unsigned xb_ld(unsigned* p)              { return __hip_atomic_load(p, __ATOMIC_RELAXED, __HIP_MEMORY_SCOPE_AGENT); }
; __device__ __forceinline__ unsigned xb_add(unsigned* p, unsigned v) { return __hip_atomic_fetch_add(p, v, __ATOMIC_RELAXED, __HIP_MEMORY_SCOPE_AGENT); }
; #define XB_SPIN(cond, bar) do { unsigned _sp = 0; while (cond) { __builtin_amdgcn_s_sleep(1); \
;     if ((++_sp & 255u) == 0u) { if (xb_ld(&(bar)[XB_TMO])) break; if (_sp > XB_SPIN_CAP) { atomicAdd(&(bar)[XB_TMO], 1u); break; } } } } while (0)
; __device__ __forceinline__ void xcd_barrier(const XcdBarrier& b, int wv) {
;     ...
;         const unsigned old = xb_add(&bar[XB_XSUB(bx)], 1u);
;         const unsigned gen = old / nloc;
;         if (old + 1u == (gen + 1u) * nloc) {
;     ...
;             XB_SPIN(xb_ld(&bar[XB_XGEN(bx)]) == gen, bar);
.LBB0_243:
	s_or_b64 exec, exec, s[14:15]
	v_cvt_f32_u32_e32 v5, v3
	s_waitcnt vmcnt(0)
	v_readfirstlane_b32 s10, v4
	v_sub_u32_e32 v4, 0, v3
	v_rcp_iflag_f32_e32 v5, v5
	v_add_u32_e32 v6, s10, v1
	v_mul_f32_e32 v5, 0x4f7ffffe, v5
	v_cvt_u32_f32_e32 v5, v5
	v_mul_lo_u32 v1, v4, v5
	v_mul_hi_u32 v1, v5, v1
	v_add_u32_e32 v1, v5, v1
	v_mul_hi_u32 v1, v6, v1
	v_mul_lo_u32 v4, v1, v3
	v_sub_u32_e32 v4, v6, v4
	v_add_u32_e32 v5, 1, v1
	v_cmp_ge_u32_e32 vcc, v4, v3
	s_nop 1
	v_cndmask_b32_e32 v1, v1, v5, vcc
	v_sub_u32_e32 v5, v4, v3
	v_cndmask_b32_e32 v4, v4, v5, vcc
	v_add_u32_e32 v5, 1, v1
	v_cmp_ge_u32_e32 vcc, v4, v3
	v_add_u32_e32 v4, 1, v6
	s_nop 0
	v_cndmask_b32_e32 v1, v1, v5, vcc
	v_mul_lo_u32 v5, v3, v1
	v_add_u32_e32 v3, v5, v3
	v_cmp_ne_u32_e32 vcc, v4, v3
	s_and_saveexec_b64 s[10:11], vcc
	s_xor_b64 s[10:11], exec, s[10:11]
	s_cbranch_execz .LBB0_257
	s_movk_i32 s36, 0xd00
	v_mad_u32_u24 v2, v1, v2, v2
	s_nop 0
	v_readfirstlane_b32 s98, v2
	s_lshl_b64 s[14:15], s[36:37], 2
	s_add_u32 s16, s82, s14
	s_addc_u32 s17, s83, s15
	s_waitcnt lgkmcnt(0)
	global_load_dword v2, v0, s[16:17] sc1
	s_waitcnt vmcnt(0)
	v_cmp_gt_u32_e32 vcc, s98, v2
	s_and_saveexec_b64 s[14:15], vcc
	s_cbranch_execz .LBB0_256
	s_mov_b32 s36, 1
	s_mov_b64 s[20:21], 0
	s_branch .LBB0_247

; __device__ __forceinline__ unsigned xb_ld(unsigned* p)              { return __hip_atomic_load(p, __ATOMIC_RELAXED, __HIP_MEMORY_SCOPE_AGENT); }
; #define XB_SPIN(cond, bar) do { unsigned _sp = 0; while (cond) { __builtin_amdgcn_s_sleep(1); \
;     if ((++_sp & 255u) == 0u) { if (xb_ld(&(bar)[XB_TMO])) break; if (_sp > XB_SPIN_CAP) { atomicAdd(&(bar)[XB_TMO], 1u); break; } } } } while (0)
; __device__ __forceinline__ void xcd_barrier(const XcdBarrier& b, int wv) {
;     ...
;             XB_SPIN(xb_ld(&bar[XB_XGEN(bx)]) == gen, bar);
.LBB0_249:
	global_load_dword v2, v0, s[16:17] sc1
	s_add_i32 s36, s36, 1
	s_mov_b64 s[54:55], -1
	s_waitcnt vmcnt(0)
	v_cmp_le_u32_e32 vcc, s98, v2
	s_orn2_b64 s[52:53], vcc, exec
	s_branch .LBB0_246

; __device__ __forceinline__ unsigned xb_ld(unsigned* p)              { return __hip_atomic_load(p, __ATOMIC_RELAXED, __HIP_MEMORY_SCOPE_AGENT); }
; __device__ __forceinline__ unsigned xb_add(unsigned* p, unsigned v) { return __hip_atomic_fetch_add(p, v, __ATOMIC_RELAXED, __HIP_MEMORY_SCOPE_AGENT); }
; #define XB_SPIN(cond, bar) do { unsigned _sp = 0; while (cond) { __builtin_amdgcn_s_sleep(1); \
;     if ((++_sp & 255u) == 0u) { if (xb_ld(&(bar)[XB_TMO])) break; if (_sp > XB_SPIN_CAP) { atomicAdd(&(bar)[XB_TMO], 1u); break; } } } } while (0)
; __device__ __forceinline__ void xcd_barrier(const XcdBarrier& b, int wv) {
;     ...
;             const unsigned og = xb_add(&bar[XB_TOP], 1u);
;             const unsigned tg = og / nx;
;             if (og + 1u == (tg + 1u) * nx) xb_add(&bar[XB_TOPGEN], 1u);
;             else XB_SPIN(xb_ld(&bar[XB_TOPGEN]) == tg, bar);
.LBB0_260:
	s_or_b64 exec, exec, s[14:15]
	s_waitcnt vmcnt(0)
	v_readfirstlane_b32 s10, v3
	v_sub_u32_e32 v4, 0, v2
	s_mov_b64 s[14:15], -1
	v_add_u32_e32 v3, s10, v1
	v_cvt_f32_u32_e32 v1, v2
	v_rcp_iflag_f32_e32 v1, v1
	s_nop 0
	v_mul_f32_e32 v1, 0x4f7ffffe, v1
	v_cvt_u32_f32_e32 v1, v1
	v_mul_lo_u32 v4, v4, v1
	v_mul_hi_u32 v4, v1, v4
	v_add_u32_e32 v1, v1, v4
	v_mul_hi_u32 v1, v3, v1
	v_mul_lo_u32 v4, v1, v2
	v_sub_u32_e32 v4, v3, v4
	v_cmp_ge_u32_e32 vcc, v4, v2
	v_add_u32_e32 v5, 1, v1
	v_add_u32_e32 v3, 1, v3
	v_cndmask_b32_e32 v1, v1, v5, vcc
	v_sub_u32_e32 v5, v4, v2
	v_cndmask_b32_e32 v4, v4, v5, vcc
	v_cmp_ge_u32_e32 vcc, v4, v2
	v_add_u32_e32 v4, 1, v1
	s_nop 0
	v_cndmask_b32_e32 v1, v1, v4, vcc
	v_mul_lo_u32 v4, v2, v1
	v_add_u32_e32 v2, v4, v2
	v_cmp_ne_u32_e32 vcc, v3, v2
	v_readfirstlane_b32 s98, v2
	v_mov_b64_e32 v[2:3], s[80:81]
	s_and_saveexec_b64 s[10:11], vcc
	s_cbranch_execz .LBB0_272
	global_load_dword v2, v0, s[80:81] offset:-256 sc1
	s_mov_b64 s[16:17], 0
	s_waitcnt vmcnt(0)
	v_cmp_gt_u32_e32 vcc, s98, v2
	s_and_saveexec_b64 s[14:15], vcc
	s_cbranch_execz .LBB0_271
	s_mov_b32 s36, 1
	s_branch .LBB0_264

; __device__ __forceinline__ unsigned xb_ld(unsigned* p)              { return __hip_atomic_load(p, __ATOMIC_RELAXED, __HIP_MEMORY_SCOPE_AGENT); }
; #define XB_SPIN(cond, bar) do { unsigned _sp = 0; while (cond) { __builtin_amdgcn_s_sleep(1); \
;     if ((++_sp & 255u) == 0u) { if (xb_ld(&(bar)[XB_TMO])) break; if (_sp > XB_SPIN_CAP) { atomicAdd(&(bar)[XB_TMO], 1u); break; } } } } while (0)
; __device__ __forceinline__ void xcd_barrier(const XcdBarrier& b, int wv) {
;     ...
;             else XB_SPIN(xb_ld(&bar[XB_TOPGEN]) == tg, bar);
.LBB0_266:
	global_load_dword v2, v0, s[80:81] offset:-256 sc1
	s_add_i32 s36, s36, 1
	s_mov_b64 s[52:53], -1
	s_waitcnt vmcnt(0)
	v_cmp_le_u32_e32 vcc, s98, v2
	s_orn2_b64 s[22:23], vcc, exec
	s_branch .LBB0_263

; __device__ __forceinline__ unsigned xb_ld(unsigned* p)              { return __hip_atomic_load(p, __ATOMIC_RELAXED, __HIP_MEMORY_SCOPE_AGENT); }
; __device__ __forceinline__ unsigned xb_add(unsigned* p, unsigned v) { return __hip_atomic_fetch_add(p, v, __ATOMIC_RELAXED, __HIP_MEMORY_SCOPE_AGENT); }
; #define XB_SPIN(cond, bar) do { unsigned _sp = 0; while (cond) { __builtin_amdgcn_s_sleep(1); \
;     if ((++_sp & 255u) == 0u) { if (xb_ld(&(bar)[XB_TMO])) break; if (_sp > XB_SPIN_CAP) { atomicAdd(&(bar)[XB_TMO], 1u); break; } } } } while (0)
; __device__ __forceinline__ void xcd_barrier(const XcdBarrier& b, int wv) {
;     ...
;         const unsigned old = xb_add(&bar[XB_XSUB(bx)], 1u);
;         const unsigned gen = old / nloc;
;         if (old + 1u == (gen + 1u) * nloc) {
;     ...
;             XB_SPIN(xb_ld(&bar[XB_XGEN(bx)]) == gen, bar);
.LBB0_351:
	s_or_b64 exec, exec, s[10:11]
	v_cvt_f32_u32_e32 v5, v3
	s_waitcnt vmcnt(0)
	v_readfirstlane_b32 s6, v4
	v_sub_u32_e32 v4, 0, v3
	v_rcp_iflag_f32_e32 v5, v5
	v_add_u32_e32 v6, s6, v1
	v_mul_f32_e32 v5, 0x4f7ffffe, v5
	v_cvt_u32_f32_e32 v5, v5
	v_mul_lo_u32 v1, v4, v5
	v_mul_hi_u32 v1, v5, v1
	v_add_u32_e32 v1, v5, v1
	v_mul_hi_u32 v1, v6, v1
	v_mul_lo_u32 v4, v1, v3
	v_sub_u32_e32 v4, v6, v4
	v_add_u32_e32 v5, 1, v1
	v_cmp_ge_u32_e32 vcc, v4, v3
	s_nop 1
	v_cndmask_b32_e32 v1, v1, v5, vcc
	v_sub_u32_e32 v5, v4, v3
	v_cndmask_b32_e32 v4, v4, v5, vcc
	v_add_u32_e32 v5, 1, v1
	v_cmp_ge_u32_e32 vcc, v4, v3
	v_add_u32_e32 v4, 1, v6
	s_nop 0
	v_cndmask_b32_e32 v1, v1, v5, vcc
	v_mul_lo_u32 v5, v3, v1
	v_add_u32_e32 v3, v5, v3
	v_cmp_ne_u32_e32 vcc, v4, v3
	s_and_saveexec_b64 s[6:7], vcc
	s_xor_b64 s[6:7], exec, s[6:7]
	s_cbranch_execz .LBB0_365
	s_movk_i32 s36, 0xd00
	v_mad_u32_u24 v2, v1, v2, v2
	s_nop 0
	v_readfirstlane_b32 s98, v2
	s_lshl_b64 s[10:11], s[36:37], 2
	s_add_u32 s14, s82, s10
	s_addc_u32 s15, s83, s11
	s_waitcnt lgkmcnt(0)
	global_load_dword v2, v0, s[14:15] sc1
	s_waitcnt vmcnt(0)
	v_cmp_gt_u32_e32 vcc, s98, v2
	s_and_saveexec_b64 s[10:11], vcc
	s_cbranch_execz .LBB0_364
	s_mov_b32 s36, 1
	s_mov_b64 s[16:17], 0
	s_branch .LBB0_355

; __device__ __forceinline__ unsigned xb_ld(unsigned* p)              { return __hip_atomic_load(p, __ATOMIC_RELAXED, __HIP_MEMORY_SCOPE_AGENT); }
; #define XB_SPIN(cond, bar) do { unsigned _sp = 0; while (cond) { __builtin_amdgcn_s_sleep(1); \
;     if ((++_sp & 255u) == 0u) { if (xb_ld(&(bar)[XB_TMO])) break; if (_sp > XB_SPIN_CAP) { atomicAdd(&(bar)[XB_TMO], 1u); break; } } } } while (0)
; __device__ __forceinline__ void xcd_barrier(const XcdBarrier& b, int wv) {
;     ...
;             XB_SPIN(xb_ld(&bar[XB_XGEN(bx)]) == gen, bar);
.LBB0_357:
	global_load_dword v2, v0, s[14:15] sc1
	s_add_i32 s36, s36, 1
	s_mov_b64 s[52:53], -1
	s_waitcnt vmcnt(0)
	v_cmp_le_u32_e32 vcc, s98, v2
	s_orn2_b64 s[22:23], vcc, exec
	s_branch .LBB0_354

; __device__ __forceinline__ unsigned xb_ld(unsigned* p)              { return __hip_atomic_load(p, __ATOMIC_RELAXED, __HIP_MEMORY_SCOPE_AGENT); }
; __device__ __forceinline__ unsigned xb_add(unsigned* p, unsigned v) { return __hip_atomic_fetch_add(p, v, __ATOMIC_RELAXED, __HIP_MEMORY_SCOPE_AGENT); }
; #define XB_SPIN(cond, bar) do { unsigned _sp = 0; while (cond) { __builtin_amdgcn_s_sleep(1); \
;     if ((++_sp & 255u) == 0u) { if (xb_ld(&(bar)[XB_TMO])) break; if (_sp > XB_SPIN_CAP) { atomicAdd(&(bar)[XB_TMO], 1u); break; } } } } while (0)
; __device__ __forceinline__ void xcd_barrier(const XcdBarrier& b, int wv) {
;     ...
;             const unsigned og = xb_add(&bar[XB_TOP], 1u);
;             const unsigned tg = og / nx;
;             if (og + 1u == (tg + 1u) * nx) xb_add(&bar[XB_TOPGEN], 1u);
;             else XB_SPIN(xb_ld(&bar[XB_TOPGEN]) == tg, bar);
.LBB0_368:
	s_or_b64 exec, exec, s[10:11]
	s_waitcnt vmcnt(0)
	v_readfirstlane_b32 s6, v3
	v_sub_u32_e32 v4, 0, v2
	s_mov_b64 s[10:11], -1
	v_add_u32_e32 v3, s6, v1
	v_cvt_f32_u32_e32 v1, v2
	v_rcp_iflag_f32_e32 v1, v1
	s_nop 0
	v_mul_f32_e32 v1, 0x4f7ffffe, v1
	v_cvt_u32_f32_e32 v1, v1
	v_mul_lo_u32 v4, v4, v1
	v_mul_hi_u32 v4, v1, v4
	v_add_u32_e32 v1, v1, v4
	v_mul_hi_u32 v1, v3, v1
	v_mul_lo_u32 v4, v1, v2
	v_sub_u32_e32 v4, v3, v4
	v_cmp_ge_u32_e32 vcc, v4, v2
	v_add_u32_e32 v5, 1, v1
	v_add_u32_e32 v3, 1, v3
	v_cndmask_b32_e32 v1, v1, v5, vcc
	v_sub_u32_e32 v5, v4, v2
	v_cndmask_b32_e32 v4, v4, v5, vcc
	v_cmp_ge_u32_e32 vcc, v4, v2
	v_add_u32_e32 v4, 1, v1
	s_nop 0
	v_cndmask_b32_e32 v1, v1, v4, vcc
	v_mul_lo_u32 v4, v2, v1
	v_add_u32_e32 v2, v4, v2
	v_cmp_ne_u32_e32 vcc, v3, v2
	v_readfirstlane_b32 s98, v2
	v_mov_b64_e32 v[2:3], s[80:81]
	s_and_saveexec_b64 s[6:7], vcc
	s_cbranch_execz .LBB0_380
	global_load_dword v2, v0, s[80:81] offset:-256 sc1
	s_mov_b64 s[14:15], 0
	s_waitcnt vmcnt(0)
	v_cmp_gt_u32_e32 vcc, s98, v2
	s_and_saveexec_b64 s[10:11], vcc
	s_cbranch_execz .LBB0_379
	s_mov_b32 s36, 1
	s_branch .LBB0_372

; __device__ __forceinline__ unsigned xb_ld(unsigned* p)              { return __hip_atomic_load(p, __ATOMIC_RELAXED, __HIP_MEMORY_SCOPE_AGENT); }
; #define XB_SPIN(cond, bar) do { unsigned _sp = 0; while (cond) { __builtin_amdgcn_s_sleep(1); \
;     if ((++_sp & 255u) == 0u) { if (xb_ld(&(bar)[XB_TMO])) break; if (_sp > XB_SPIN_CAP) { atomicAdd(&(bar)[XB_TMO], 1u); break; } } } } while (0)
; __device__ __forceinline__ void xcd_barrier(const XcdBarrier& b, int wv) {
;     ...
;             else XB_SPIN(xb_ld(&bar[XB_TOPGEN]) == tg, bar);
.LBB0_374:
	global_load_dword v2, v0, s[80:81] offset:-256 sc1
	s_add_i32 s36, s36, 1
	s_mov_b64 s[22:23], -1
	s_waitcnt vmcnt(0)
	v_cmp_le_u32_e32 vcc, s98, v2
	s_orn2_b64 s[20:21], vcc, exec
	s_branch .LBB0_371

; __device__ __forceinline__ unsigned xb_ld(unsigned* p)              { return __hip_atomic_load(p, __ATOMIC_RELAXED, __HIP_MEMORY_SCOPE_AGENT); }
; __device__ __forceinline__ unsigned xb_add(unsigned* p, unsigned v) { return __hip_atomic_fetch_add(p, v, __ATOMIC_RELAXED, __HIP_MEMORY_SCOPE_AGENT); }
; #define XB_SPIN(cond, bar) do { unsigned _sp = 0; while (cond) { __builtin_amdgcn_s_sleep(1); \
;     if ((++_sp & 255u) == 0u) { if (xb_ld(&(bar)[XB_TMO])) break; if (_sp > XB_SPIN_CAP) { atomicAdd(&(bar)[XB_TMO], 1u); break; } } } } while (0)
; __device__ __forceinline__ void xcd_barrier(const XcdBarrier& b, int wv) {
;     ...
;         const unsigned old = xb_add(&bar[XB_XSUB(bx)], 1u);
;         const unsigned gen = old / nloc;
;         if (old + 1u == (gen + 1u) * nloc) {
;     ...
;             XB_SPIN(xb_ld(&bar[XB_XGEN(bx)]) == gen, bar);
.LBB0_525:
	s_or_b64 exec, exec, s[6:7]
	v_cvt_f32_u32_e32 v5, v3
	s_waitcnt vmcnt(0)
	v_readfirstlane_b32 s4, v4
	v_sub_u32_e32 v4, 0, v3
	v_rcp_iflag_f32_e32 v5, v5
	v_add_u32_e32 v6, s4, v1
	v_mul_f32_e32 v5, 0x4f7ffffe, v5
	v_cvt_u32_f32_e32 v5, v5
	v_mul_lo_u32 v1, v4, v5
	v_mul_hi_u32 v1, v5, v1
	v_add_u32_e32 v1, v5, v1
	v_mul_hi_u32 v1, v6, v1
	v_mul_lo_u32 v4, v1, v3
	v_sub_u32_e32 v4, v6, v4
	v_add_u32_e32 v5, 1, v1
	v_cmp_ge_u32_e32 vcc, v4, v3
	s_nop 1
	v_cndmask_b32_e32 v1, v1, v5, vcc
	v_sub_u32_e32 v5, v4, v3
	v_cndmask_b32_e32 v4, v4, v5, vcc
	v_add_u32_e32 v5, 1, v1
	v_cmp_ge_u32_e32 vcc, v4, v3
	v_add_u32_e32 v4, 1, v6
	s_nop 0
	v_cndmask_b32_e32 v1, v1, v5, vcc
	v_mul_lo_u32 v5, v3, v1
	v_add_u32_e32 v3, v5, v3
	v_cmp_ne_u32_e32 vcc, v4, v3
	s_and_saveexec_b64 s[4:5], vcc
	s_xor_b64 s[4:5], exec, s[4:5]
	s_cbranch_execz .LBB0_539
	s_movk_i32 s36, 0xd00
	v_mad_u32_u24 v2, v1, v2, v2
	s_nop 0
	v_readfirstlane_b32 s98, v2
	s_lshl_b64 s[6:7], s[36:37], 2
	s_add_u32 s8, s82, s6
	s_addc_u32 s9, s83, s7
	s_waitcnt lgkmcnt(0)
	global_load_dword v2, v0, s[8:9] sc1
	s_waitcnt vmcnt(0)
	v_cmp_gt_u32_e32 vcc, s98, v2
	s_and_saveexec_b64 s[6:7], vcc
	s_cbranch_execz .LBB0_538
	s_mov_b32 s36, 1
	s_mov_b64 s[10:11], 0
	s_branch .LBB0_529

; __device__ __forceinline__ unsigned xb_ld(unsigned* p)              { return __hip_atomic_load(p, __ATOMIC_RELAXED, __HIP_MEMORY_SCOPE_AGENT); }
; #define XB_SPIN(cond, bar) do { unsigned _sp = 0; while (cond) { __builtin_amdgcn_s_sleep(1); \
;     if ((++_sp & 255u) == 0u) { if (xb_ld(&(bar)[XB_TMO])) break; if (_sp > XB_SPIN_CAP) { atomicAdd(&(bar)[XB_TMO], 1u); break; } } } } while (0)
; __device__ __forceinline__ void xcd_barrier(const XcdBarrier& b, int wv) {
;     ...
;             XB_SPIN(xb_ld(&bar[XB_XGEN(bx)]) == gen, bar);
.LBB0_531:
	global_load_dword v2, v0, s[8:9] sc1
	s_add_i32 s36, s36, 1
	s_mov_b64 s[16:17], -1
	s_waitcnt vmcnt(0)
	v_cmp_le_u32_e32 vcc, s98, v2
	s_orn2_b64 s[14:15], vcc, exec
	s_branch .LBB0_528

; __device__ __forceinline__ unsigned xb_ld(unsigned* p)              { return __hip_atomic_load(p, __ATOMIC_RELAXED, __HIP_MEMORY_SCOPE_AGENT); }
; __device__ __forceinline__ unsigned xb_add(unsigned* p, unsigned v) { return __hip_atomic_fetch_add(p, v, __ATOMIC_RELAXED, __HIP_MEMORY_SCOPE_AGENT); }
; #define XB_SPIN(cond, bar) do { unsigned _sp = 0; while (cond) { __builtin_amdgcn_s_sleep(1); \
;     if ((++_sp & 255u) == 0u) { if (xb_ld(&(bar)[XB_TMO])) break; if (_sp > XB_SPIN_CAP) { atomicAdd(&(bar)[XB_TMO], 1u); break; } } } } while (0)
; __device__ __forceinline__ void xcd_barrier(const XcdBarrier& b, int wv) {
;     ...
;             const unsigned og = xb_add(&bar[XB_TOP], 1u);
;             const unsigned tg = og / nx;
;             if (og + 1u == (tg + 1u) * nx) xb_add(&bar[XB_TOPGEN], 1u);
;             else XB_SPIN(xb_ld(&bar[XB_TOPGEN]) == tg, bar);
.LBB0_542:
	s_or_b64 exec, exec, s[6:7]
	s_waitcnt vmcnt(0)
	v_readfirstlane_b32 s4, v3
	v_sub_u32_e32 v4, 0, v2
	s_mov_b64 s[6:7], -1
	v_add_u32_e32 v3, s4, v1
	v_cvt_f32_u32_e32 v1, v2
	v_rcp_iflag_f32_e32 v1, v1
	s_nop 0
	v_mul_f32_e32 v1, 0x4f7ffffe, v1
	v_cvt_u32_f32_e32 v1, v1
	v_mul_lo_u32 v4, v4, v1
	v_mul_hi_u32 v4, v1, v4
	v_add_u32_e32 v1, v1, v4
	v_mul_hi_u32 v1, v3, v1
	v_mul_lo_u32 v4, v1, v2
	v_sub_u32_e32 v4, v3, v4
	v_cmp_ge_u32_e32 vcc, v4, v2
	v_add_u32_e32 v5, 1, v1
	v_add_u32_e32 v3, 1, v3
	v_cndmask_b32_e32 v1, v1, v5, vcc
	v_sub_u32_e32 v5, v4, v2
	v_cndmask_b32_e32 v4, v4, v5, vcc
	v_cmp_ge_u32_e32 vcc, v4, v2
	v_add_u32_e32 v4, 1, v1
	s_nop 0
	v_cndmask_b32_e32 v1, v1, v4, vcc
	v_mul_lo_u32 v4, v2, v1
	v_add_u32_e32 v2, v4, v2
	v_cmp_ne_u32_e32 vcc, v3, v2
	v_readfirstlane_b32 s98, v2
	v_mov_b64_e32 v[2:3], s[80:81]
	s_and_saveexec_b64 s[4:5], vcc
	s_cbranch_execz .LBB0_554
	global_load_dword v2, v0, s[80:81] offset:-256 sc1
	s_mov_b64 s[8:9], 0
	s_waitcnt vmcnt(0)
	v_cmp_gt_u32_e32 vcc, s98, v2
	s_and_saveexec_b64 s[6:7], vcc
	s_cbranch_execz .LBB0_553
	s_mov_b32 s36, 1
	s_branch .LBB0_546

; __device__ __forceinline__ unsigned xb_ld(unsigned* p)              { return __hip_atomic_load(p, __ATOMIC_RELAXED, __HIP_MEMORY_SCOPE_AGENT); }
; #define XB_SPIN(cond, bar) do { unsigned _sp = 0; while (cond) { __builtin_amdgcn_s_sleep(1); \
;     if ((++_sp & 255u) == 0u) { if (xb_ld(&(bar)[XB_TMO])) break; if (_sp > XB_SPIN_CAP) { atomicAdd(&(bar)[XB_TMO], 1u); break; } } } } while (0)
; __device__ __forceinline__ void xcd_barrier(const XcdBarrier& b, int wv) {
;     ...
;             else XB_SPIN(xb_ld(&bar[XB_TOPGEN]) == tg, bar);
.LBB0_548:
	global_load_dword v2, v0, s[80:81] offset:-256 sc1
	s_add_i32 s36, s36, 1
	s_mov_b64 s[14:15], -1
	s_waitcnt vmcnt(0)
	v_cmp_le_u32_e32 vcc, s98, v2
	s_orn2_b64 s[12:13], vcc, exec
	s_branch .LBB0_545

; __device__ __forceinline__ unsigned xb_ld(unsigned* p)              { return __hip_atomic_load(p, __ATOMIC_RELAXED, __HIP_MEMORY_SCOPE_AGENT); }
; __device__ __forceinline__ unsigned xb_add(unsigned* p, unsigned v) { return __hip_atomic_fetch_add(p, v, __ATOMIC_RELAXED, __HIP_MEMORY_SCOPE_AGENT); }
; #define XB_SPIN(cond, bar) do { unsigned _sp = 0; while (cond) { __builtin_amdgcn_s_sleep(1); \
;     if ((++_sp & 255u) == 0u) { if (xb_ld(&(bar)[XB_TMO])) break; if (_sp > XB_SPIN_CAP) { atomicAdd(&(bar)[XB_TMO], 1u); break; } } } } while (0)
; __device__ __forceinline__ void xcd_barrier(const XcdBarrier& b, int wv) {
;     ...
;         const unsigned old = xb_add(&bar[XB_XSUB(bx)], 1u);
;         const unsigned gen = old / nloc;
;         if (old + 1u == (gen + 1u) * nloc) {
;     ...
;             XB_SPIN(xb_ld(&bar[XB_XGEN(bx)]) == gen, bar);
.LBB0_764:
	s_or_b64 exec, exec, s[6:7]
	v_cvt_f32_u32_e32 v5, v3
	s_waitcnt vmcnt(0)
	v_readfirstlane_b32 s4, v4
	v_sub_u32_e32 v4, 0, v3
	v_rcp_iflag_f32_e32 v5, v5
	v_add_u32_e32 v6, s4, v1
	v_mul_f32_e32 v5, 0x4f7ffffe, v5
	v_cvt_u32_f32_e32 v5, v5
	v_mul_lo_u32 v1, v4, v5
	v_mul_hi_u32 v1, v5, v1
	v_add_u32_e32 v1, v5, v1
	v_mul_hi_u32 v1, v6, v1
	v_mul_lo_u32 v4, v1, v3
	v_sub_u32_e32 v4, v6, v4
	v_add_u32_e32 v5, 1, v1
	v_cmp_ge_u32_e32 vcc, v4, v3
	s_nop 1
	v_cndmask_b32_e32 v1, v1, v5, vcc
	v_sub_u32_e32 v5, v4, v3
	v_cndmask_b32_e32 v4, v4, v5, vcc
	v_add_u32_e32 v5, 1, v1
	v_cmp_ge_u32_e32 vcc, v4, v3
	v_add_u32_e32 v4, 1, v6
	s_nop 0
	v_cndmask_b32_e32 v1, v1, v5, vcc
	v_mul_lo_u32 v5, v3, v1
	v_add_u32_e32 v3, v5, v3
	v_cmp_ne_u32_e32 vcc, v4, v3
	s_and_saveexec_b64 s[4:5], vcc
	s_xor_b64 s[4:5], exec, s[4:5]
	s_cbranch_execz .LBB0_778
	s_movk_i32 s36, 0xd00
	v_mad_u32_u24 v2, v1, v2, v2
	s_nop 0
	v_readfirstlane_b32 s98, v2
	s_lshl_b64 s[6:7], s[36:37], 2
	s_add_u32 s8, s82, s6
	s_addc_u32 s9, s83, s7
	s_waitcnt lgkmcnt(0)
	global_load_dword v2, v0, s[8:9] sc1
	s_waitcnt vmcnt(0)
	v_cmp_gt_u32_e32 vcc, s98, v2
	s_and_saveexec_b64 s[6:7], vcc
	s_cbranch_execz .LBB0_777
	s_mov_b32 s36, 1
	s_mov_b64 s[12:13], 0
	s_branch .LBB0_768

; __device__ __forceinline__ unsigned xb_ld(unsigned* p)              { return __hip_atomic_load(p, __ATOMIC_RELAXED, __HIP_MEMORY_SCOPE_AGENT); }
; #define XB_SPIN(cond, bar) do { unsigned _sp = 0; while (cond) { __builtin_amdgcn_s_sleep(1); \
;     if ((++_sp & 255u) == 0u) { if (xb_ld(&(bar)[XB_TMO])) break; if (_sp > XB_SPIN_CAP) { atomicAdd(&(bar)[XB_TMO], 1u); break; } } } } while (0)
; __device__ __forceinline__ void xcd_barrier(const XcdBarrier& b, int wv) {
;     ...
;             XB_SPIN(xb_ld(&bar[XB_XGEN(bx)]) == gen, bar);
.LBB0_770:
	global_load_dword v2, v0, s[8:9] sc1
	s_add_i32 s36, s36, 1
	s_mov_b64 s[52:53], -1
	s_waitcnt vmcnt(0)
	v_cmp_le_u32_e32 vcc, s98, v2
	s_orn2_b64 s[16:17], vcc, exec
	s_branch .LBB0_767

; __device__ __forceinline__ unsigned xb_ld(unsigned* p)              { return __hip_atomic_load(p, __ATOMIC_RELAXED, __HIP_MEMORY_SCOPE_AGENT); }
; #define XB_SPIN(cond, bar) do { unsigned _sp = 0; while (cond) { __builtin_amdgcn_s_sleep(1); \
;     if ((++_sp & 255u) == 0u) { if (xb_ld(&(bar)[XB_TMO])) break; if (_sp > XB_SPIN_CAP) { atomicAdd(&(bar)[XB_TMO], 1u); break; } } } } while (0)
; __device__ __forceinline__ void xcd_barrier(const XcdBarrier& b, int wv) {
;     ...
;             else XB_SPIN(xb_ld(&bar[XB_TOPGEN]) == tg, bar);
.LBB0_787:
	global_load_dword v2, v0, s[80:81] offset:-256 sc1
	s_add_i32 s36, s36, 1
	s_mov_b64 s[16:17], -1
	s_waitcnt vmcnt(0)
	v_cmp_le_u32_e32 vcc, s98, v2
	s_orn2_b64 s[14:15], vcc, exec
	s_branch .LBB0_784

; __device__ __forceinline__ unsigned xb_ld(unsigned* p)              { return __hip_atomic_load(p, __ATOMIC_RELAXED, __HIP_MEMORY_SCOPE_AGENT); }
; __device__ __forceinline__ unsigned xb_add(unsigned* p, unsigned v) { return __hip_atomic_fetch_add(p, v, __ATOMIC_RELAXED, __HIP_MEMORY_SCOPE_AGENT); }
; #define XB_SPIN(cond, bar) do { unsigned _sp = 0; while (cond) { __builtin_amdgcn_s_sleep(1); \
;     if ((++_sp & 255u) == 0u) { if (xb_ld(&(bar)[XB_TMO])) break; if (_sp > XB_SPIN_CAP) { atomicAdd(&(bar)[XB_TMO], 1u); break; } } } } while (0)
; __device__ __forceinline__ void xcd_barrier(const XcdBarrier& b, int wv) {
;     ...
;         const unsigned old = xb_add(&bar[XB_XSUB(bx)], 1u);
;         const unsigned gen = old / nloc;
;         if (old + 1u == (gen + 1u) * nloc) {
;     ...
;             XB_SPIN(xb_ld(&bar[XB_XGEN(bx)]) == gen, bar);
.LBB0_818:
	s_or_b64 exec, exec, s[10:11]
	v_cvt_f32_u32_e32 v8, v6
	s_waitcnt vmcnt(0)
	v_readfirstlane_b32 s8, v7
	v_sub_u32_e32 v7, 0, v6
	v_rcp_iflag_f32_e32 v8, v8
	v_add_u32_e32 v9, s8, v5
	v_mul_f32_e32 v8, 0x4f7ffffe, v8
	v_cvt_u32_f32_e32 v8, v8
	v_mul_lo_u32 v5, v7, v8
	v_mul_hi_u32 v5, v8, v5
	v_add_u32_e32 v5, v8, v5
	v_mul_hi_u32 v5, v9, v5
	v_mul_lo_u32 v7, v5, v6
	v_sub_u32_e32 v7, v9, v7
	v_add_u32_e32 v8, 1, v5
	v_cmp_ge_u32_e32 vcc, v7, v6
	s_nop 1
	v_cndmask_b32_e32 v5, v5, v8, vcc
	v_sub_u32_e32 v8, v7, v6
	v_cndmask_b32_e32 v7, v7, v8, vcc
	v_add_u32_e32 v8, 1, v5
	v_cmp_ge_u32_e32 vcc, v7, v6
	v_add_u32_e32 v7, 1, v9
	s_nop 0
	v_cndmask_b32_e32 v5, v5, v8, vcc
	v_mul_lo_u32 v8, v6, v5
	v_add_u32_e32 v6, v8, v6
	v_cmp_ne_u32_e32 vcc, v7, v6
	s_and_saveexec_b64 s[8:9], vcc
	s_xor_b64 s[8:9], exec, s[8:9]
	s_cbranch_execz .LBB0_832
	s_movk_i32 s10, 0xd00
	v_mad_u32_u24 v6, v5, v4, v4
	s_nop 0
	v_readfirstlane_b32 s98, v6
	s_mov_b32 s11, 0
	s_lshl_b64 s[10:11], s[10:11], 2
	s_add_u32 s12, s82, s10
	s_addc_u32 s13, s83, s11
	s_waitcnt lgkmcnt(0)
	v_mov_b32_e32 v4, 0
	global_load_dword v6, v4, s[12:13] sc1
	s_waitcnt vmcnt(0)
	v_cmp_gt_u32_e32 vcc, s98, v6
	s_and_saveexec_b64 s[10:11], vcc
	s_cbranch_execz .LBB0_831
	s_mov_b32 s25, 1
	s_mov_b64 s[14:15], 0
	s_branch .LBB0_822

; __device__ __forceinline__ unsigned xb_ld(unsigned* p)              { return __hip_atomic_load(p, __ATOMIC_RELAXED, __HIP_MEMORY_SCOPE_AGENT); }
; #define XB_SPIN(cond, bar) do { unsigned _sp = 0; while (cond) { __builtin_amdgcn_s_sleep(1); \
;     if ((++_sp & 255u) == 0u) { if (xb_ld(&(bar)[XB_TMO])) break; if (_sp > XB_SPIN_CAP) { atomicAdd(&(bar)[XB_TMO], 1u); break; } } } } while (0)
; __device__ __forceinline__ void xcd_barrier(const XcdBarrier& b, int wv) {
;     ...
;             XB_SPIN(xb_ld(&bar[XB_XGEN(bx)]) == gen, bar);
.LBB0_824:
	global_load_dword v6, v4, s[12:13] sc1
	s_add_i32 s25, s25, 1
	s_mov_b64 s[20:21], -1
	s_waitcnt vmcnt(0)
	v_cmp_le_u32_e32 vcc, s98, v6
	s_orn2_b64 s[18:19], vcc, exec
	s_branch .LBB0_821

; __device__ __forceinline__ unsigned xb_ld(unsigned* p)              { return __hip_atomic_load(p, __ATOMIC_RELAXED, __HIP_MEMORY_SCOPE_AGENT); }
; __device__ __forceinline__ unsigned xb_add(unsigned* p, unsigned v) { return __hip_atomic_fetch_add(p, v, __ATOMIC_RELAXED, __HIP_MEMORY_SCOPE_AGENT); }
; #define XB_SPIN(cond, bar) do { unsigned _sp = 0; while (cond) { __builtin_amdgcn_s_sleep(1); \
;     if ((++_sp & 255u) == 0u) { if (xb_ld(&(bar)[XB_TMO])) break; if (_sp > XB_SPIN_CAP) { atomicAdd(&(bar)[XB_TMO], 1u); break; } } } } while (0)
; __device__ __forceinline__ void xcd_barrier(const XcdBarrier& b, int wv) {
;     ...
;             const unsigned og = xb_add(&bar[XB_TOP], 1u);
;             const unsigned tg = og / nx;
;             if (og + 1u == (tg + 1u) * nx) xb_add(&bar[XB_TOPGEN], 1u);
;             else XB_SPIN(xb_ld(&bar[XB_TOPGEN]) == tg, bar);
.LBB0_835:
	s_or_b64 exec, exec, s[10:11]
	v_cvt_f32_u32_e32 v7, v4
	s_waitcnt vmcnt(0)
	v_readfirstlane_b32 s8, v6
	s_mov_b64 s[10:11], -1
	v_rcp_iflag_f32_e32 v7, v7
	v_add_u32_e32 v5, s8, v5
	v_add_u32_e32 v8, 1, v5
	v_mul_f32_e32 v6, 0x4f7ffffe, v7
	v_cvt_u32_f32_e32 v6, v6
	v_sub_u32_e32 v7, 0, v4
	v_mul_lo_u32 v7, v7, v6
	v_mul_hi_u32 v7, v6, v7
	v_add_u32_e32 v6, v6, v7
	v_mul_hi_u32 v6, v5, v6
	v_mul_lo_u32 v7, v6, v4
	v_sub_u32_e32 v5, v5, v7
	v_add_u32_e32 v9, 1, v6
	v_cmp_ge_u32_e32 vcc, v5, v4
	v_sub_u32_e32 v7, v5, v4
	s_nop 0
	v_cndmask_b32_e32 v6, v6, v9, vcc
	v_cndmask_b32_e32 v5, v5, v7, vcc
	v_add_u32_e32 v7, 1, v6
	v_cmp_ge_u32_e32 vcc, v5, v4
	s_nop 1
	v_cndmask_b32_e32 v6, v6, v7, vcc
	v_mul_lo_u32 v5, v4, v6
	v_add_u32_e32 v4, v5, v4
	v_cmp_ne_u32_e32 vcc, v8, v4
	v_readfirstlane_b32 s98, v4
	v_mov_b64_e32 v[4:5], s[80:81]
	s_and_saveexec_b64 s[8:9], vcc
	s_cbranch_execz .LBB0_847
	v_mov_b32_e32 v4, 0
	global_load_dword v5, v4, s[80:81] offset:-256 sc1
	s_mov_b64 s[12:13], 0
	s_waitcnt vmcnt(0)
	v_cmp_gt_u32_e32 vcc, s98, v5
	s_and_saveexec_b64 s[10:11], vcc
	s_cbranch_execz .LBB0_846
	s_mov_b32 s22, 1
	s_branch .LBB0_839

; __device__ __forceinline__ unsigned xb_ld(unsigned* p)              { return __hip_atomic_load(p, __ATOMIC_RELAXED, __HIP_MEMORY_SCOPE_AGENT); }
; #define XB_SPIN(cond, bar) do { unsigned _sp = 0; while (cond) { __builtin_amdgcn_s_sleep(1); \
;     if ((++_sp & 255u) == 0u) { if (xb_ld(&(bar)[XB_TMO])) break; if (_sp > XB_SPIN_CAP) { atomicAdd(&(bar)[XB_TMO], 1u); break; } } } } while (0)
; __device__ __forceinline__ void xcd_barrier(const XcdBarrier& b, int wv) {
;     ...
;             else XB_SPIN(xb_ld(&bar[XB_TOPGEN]) == tg, bar);
.LBB0_841:
	global_load_dword v5, v4, s[80:81] offset:-256 sc1
	s_add_i32 s22, s22, 1
	s_mov_b64 s[16:17], -1
	s_waitcnt vmcnt(0)
	v_cmp_le_u32_e32 vcc, s98, v5
	s_orn2_b64 s[20:21], vcc, exec
	s_branch .LBB0_838
